# v19 (early unconditional next-chunk loads in mLSTM staging) + denominator column replicated so the per-step ds_bpermute broadcast is dropped
# speedup vs baseline: 1.0115x; 1.0058x over previous
; #define LBAR() do { asm volatile("s_waitcnt lgkmcnt(0)" ::: "memory"); __builtin_amdgcn_s_barrier(); asm volatile("" ::: "memory"); } while (0)
; DI void mlstm_phase(LAS unsigned char* lds, const bf16_t* proj, const float* gates, bf16_t* Hfw, bf16_t* Hbw, int G, int bid) {
;     ...
;     for (int item = bid; item < 512; item += G) {
;         const int it_ = item & 255; const bool lng = item < 256;
;         const int it = ((((it_ >> 3) >> 2) * 8 + (it_ & 7)) << 2) | ((it_ >> 3) & 3);
;         const int sl = it & 3, dir = (it >> 2) & 1, hh = (it >> 3) & 3, b = it >> 5;
;         const int S = lng ? 8192 : 4096; const int tok0 = lng ? b * 8192 : TP + b * 4096; const int nc = S >> 7;
;         bf16_t* Hout = dir ? Hbw : Hfw;
;         const int gcol = dir * 8 + hh;
;         LBAR();
.LBB0_823:
	s_waitcnt lgkmcnt(0)
	s_waitcnt vmcnt(0)
	s_barrier
	s_mov_b64 s[38:39], exec
	v_readlane_b32 s40, v255, 35
	v_readlane_b32 s41, v255, 36
	s_and_b64 s[40:41], s[38:39], s[40:41]
	s_mov_b64 exec, s[40:41]
	s_cbranch_execz .LBB0_826
	s_mov_b64 s[40:41], 0
	v_mov_b32_e32 v0, v177
	v_mov_b32_e32 v2, v176

; #define LAS __attribute__((address_space(3)))
; DI void mlstm_phase(LAS unsigned char* lds, const bf16_t* proj, const float* gates, bf16_t* Hfw, bf16_t* Hbw, int G, int bid) {
;     ...
;         if (tid < 128) { LAS unsigned* p = (LAS unsigned*)(Vs + tid * MV_STRIDE + 128); unsigned z = 0u; asm volatile("" : "+v"(z)); p[0] = 0x3F80u | z;
; #pragma unroll
;             for (int i = 1; i < 8; ++i) p[i] = z; }
.LBB0_826:
	s_or_b64 exec, exec, s[38:39]
	s_mov_b64 s[38:39], exec
	v_readlane_b32 s40, v255, 37
	v_readlane_b32 s41, v255, 38
	s_and_b64 s[40:41], s[38:39], s[40:41]
	s_mov_b64 exec, s[40:41]
	s_cbranch_execz .LBB0_828
	v_mov_b32_e32 v3, v1
	s_nop 0
	v_or_b32_e32 v2, 0x3f80, v3
	s_waitcnt vmcnt(11)
	v_mov_b32_e32 v4, v2
	ds_write_b96 v186, v[2:4] offset:128
	ds_write2_b32 v186, v3, v2 offset0:35 offset1:36
	ds_write2_b32 v186, v3, v2 offset0:37 offset1:38
	ds_write_b32 v186, v3 offset:156

; #define LAS __attribute__((address_space(3)))
; DI unsigned pk2(float lo, float hi) { f32x2 v = {lo, hi}; bf16x2_t b = __builtin_convertvector(v, bf16x2_t); return __builtin_bit_cast(unsigned, b); }
; DI float bflo(unsigned u) { return __uint_as_float(u << 16); }
; DI float bfhi(unsigned u) { return __uint_as_float(u & 0xffff0000u); }
; #define GLOAD(c) do { const float* g0 = gates + MTOK((c) * 128 + 2 * lane) * 16; const float* g1 = gates + MTOK((c) * 128 + 2 * lane + 1) * 16; \
;                 gi0 = g0[gcol]; gf0 = g0[gcol + 4]; gi1 = g1[gcol]; gf1 = g1[gcol + 4]; } while (0)
; DI void mlstm_phase(LAS unsigned char* lds, const bf16_t* proj, const float* gates, bf16_t* Hfw, bf16_t* Hbw, int G, int bid) {
;     ...
;         for (int c = 0; c < nc; ++c) {
;             const int cur = c & 1;
;             LAS float* sa = smal + cur * 388; LAS float* sM = sa + 128; LAS float* sb = sa + 256; LAS float* scl = sa + 384;
;             const float mp = scl[0], M127 = scl[1];
; #pragma unroll
;             for (int i = 0; i < 4; ++i) { const int ci = tid + 512 * i, row = ci >> 4, ch = ci & 15;
;                 *(LAS u32x4*)(Qs + row * MQ_STRIDE + ch * 16) = pq[i]; *(LAS u32x4*)(Ks + row * MQ_STRIDE + ch * 16) = pk[i]; }
; #pragma unroll
;             for (int i = 0; i < 2; ++i) { const int ci = tid + 512 * i, row = ci >> 3, ch = ci & 7;
;                 *(LAS u32x4*)(Vs + row * MV_STRIDE + ch * 16) = pv[i];
;                 const float wsv = __expf(sa[row] - M127);
;                 u32x4 w;
; #pragma unroll
;                 for (int e = 0; e < 4; ++e) w[e] = pk2(bflo(pv[i][e]) * wsv, bfhi(pv[i][e]) * wsv);
;                 *(LAS u32x4*)(VWs + row * MV_STRIDE + ch * 16) = w;
;                 if (ch == 0) { const u32x4 x0 = {pk2(wsv, 0.f), 0u, 0u, 0u}, x1 = {0u, 0u, 0u, 0u};
;                     *(LAS u32x4*)(VWs + row * MV_STRIDE + 128) = x0; *(LAS u32x4*)(VWs + row * MV_STRIDE + 144) = x1; }
;             }
;             if (c + 1 < nc) { MLOAD(c + 1); if (wid == 2) GLOAD(c + 1); }
.LBB0_836:
	v_add_u32_e32 v0, 0x80, v155
	v_sub_u32_e32 v2, 0xffffff7f, v155
	v_add_u32_e32 v0, s48, v0
	v_add_u32_e32 v2, s46, v2
	v_cndmask_b32_e64 v2, v2, v0, s[90:91]
	v_ashrrev_i32_e32 v3, 31, v2
	v_lshl_add_u64 v[2:3], v[2:3], 0, s[96:97]
	v_mad_u64_u32 v[212:213], s[92:93], v2, s33, v[138:139]
	v_add_u32_e32 v0, 0x80, v156
	v_sub_u32_e32 v2, 0xffffff7f, v156
	v_add_u32_e32 v0, s48, v0
	v_add_u32_e32 v2, s46, v2
	v_cndmask_b32_e64 v2, v2, v0, s[90:91]
	v_mad_i32_i24 v213, v3, s33, v213
	v_ashrrev_i32_e32 v3, 31, v2
	v_lshl_add_u64 v[2:3], v[2:3], 0, s[96:97]
	v_mad_u64_u32 v[214:215], s[92:93], v2, s33, v[138:139]
	v_add_u32_e32 v0, 0x80, v157
	v_sub_u32_e32 v2, 0xffffff7f, v157
	v_add_u32_e32 v0, s48, v0
	v_add_u32_e32 v2, s46, v2
	v_cndmask_b32_e64 v2, v2, v0, s[90:91]
	v_mad_i32_i24 v215, v3, s33, v215
	v_ashrrev_i32_e32 v3, 31, v2
	v_lshl_add_u64 v[2:3], v[2:3], 0, s[96:97]
	v_mad_u64_u32 v[216:217], s[92:93], v2, s33, v[138:139]
	v_add_u32_e32 v0, 0x80, v158
	v_sub_u32_e32 v2, 0xffffff7f, v158
	v_add_u32_e32 v0, s48, v0
	v_add_u32_e32 v2, s46, v2
	v_cndmask_b32_e64 v2, v2, v0, s[90:91]
	v_mad_i32_i24 v217, v3, s33, v217
	v_ashrrev_i32_e32 v3, 31, v2
	v_lshl_add_u64 v[2:3], v[2:3], 0, s[96:97]
	v_mad_u64_u32 v[218:219], s[92:93], v2, s33, v[138:139]
	v_add_u32_e32 v0, 0x80, v159
	v_sub_u32_e32 v2, 0xffffff7f, v159
	v_add_u32_e32 v0, s48, v0
	v_add_u32_e32 v2, s46, v2
	v_cndmask_b32_e64 v2, v2, v0, s[90:91]
	v_mad_i32_i24 v219, v3, s33, v219
	v_ashrrev_i32_e32 v3, 31, v2
	v_lshl_add_u64 v[2:3], v[2:3], 0, s[96:97]
	v_mad_u64_u32 v[220:221], s[92:93], v2, s33, v[140:141]
	v_add_u32_e32 v0, 0x80, v160
	v_sub_u32_e32 v2, 0xffffff7f, v160
	v_add_u32_e32 v0, s48, v0
	v_add_u32_e32 v2, s46, v2
	v_cndmask_b32_e64 v2, v2, v0, s[90:91]
	v_mad_i32_i24 v221, v3, s33, v221
	v_ashrrev_i32_e32 v3, 31, v2
	v_lshl_add_u64 v[2:3], v[2:3], 0, s[96:97]
	v_mad_u64_u32 v[222:223], s[92:93], v2, s33, v[140:141]
	v_mad_i32_i24 v223, v3, s33, v223
	s_and_b32 s50, s49, 1
	s_mul_i32 s40, s50, 0x610
	s_add_i32 s51, s40, 0
	s_add_i32 s51, s51, 0x20500
	v_mov_b32_e32 v0, s51
	ds_read_b64 v[142:143], v0 offset:1536
	v_lshl_add_u32 v224, v159, 2, s51
	v_lshl_add_u32 v225, v160, 2, s51
	ds_read_b32 v224, v224
	ds_read_b32 v225, v225
	v_add_u32_e32 v0, v149, v161
	s_waitcnt vmcnt(9)
	ds_write_b128 v179, v[4:7]
	s_waitcnt vmcnt(8)
	ds_write_b128 v179, v[8:11] offset:34816
	global_load_dwordx4 v[4:7], v[212:213], off
	global_load_dwordx4 v[8:11], v[212:213], off offset:1024
	s_waitcnt vmcnt(9)
	ds_write_b128 v180, v[12:15]
	s_waitcnt vmcnt(8)
	ds_write_b128 v180, v[16:19] offset:34816
	global_load_dwordx4 v[12:15], v[214:215], off
	global_load_dwordx4 v[16:19], v[214:215], off offset:1024
	s_waitcnt vmcnt(9)
	ds_write_b128 v181, v[20:23]
	s_waitcnt vmcnt(8)
	ds_write_b128 v181, v[24:27] offset:34816
	global_load_dwordx4 v[20:23], v[216:217], off
	global_load_dwordx4 v[24:27], v[216:217], off offset:1024
	s_waitcnt vmcnt(9)
	ds_write_b128 v182, v[28:31]
	s_waitcnt vmcnt(8)
	ds_write_b128 v182, v[32:35] offset:34816
	global_load_dwordx4 v[28:31], v[218:219], off
	global_load_dwordx4 v[32:35], v[218:219], off offset:1024
	s_waitcnt vmcnt(9)
	ds_write_b128 v0, v[36:39]
	v_lshlrev_b32_e32 v2, 16, v36
	v_and_b32_e32 v3, 0xffff0000, v36
	s_waitcnt lgkmcnt(9)
	v_sub_f32_e32 v0, v224, v143
	v_mul_f32_e32 v0, 0x3fb8aa3b, v0
	v_exp_f32_e32 v0, v0
	s_nop 0
	v_pk_mul_f32 v[2:3], v[0:1], v[2:3] op_sel_hi:[0,1]
	v_cvt_pk_bf16_f32 v84, v2, v3
	v_lshlrev_b32_e32 v2, 16, v37
	v_and_b32_e32 v3, 0xffff0000, v37
	v_pk_mul_f32 v[2:3], v[0:1], v[2:3] op_sel_hi:[0,1]
	v_cvt_pk_bf16_f32 v85, v2, v3
	v_lshlrev_b32_e32 v2, 16, v38
	v_and_b32_e32 v3, 0xffff0000, v38
	v_pk_mul_f32 v[2:3], v[0:1], v[2:3] op_sel_hi:[0,1]
	v_cvt_pk_bf16_f32 v86, v2, v3
	v_lshlrev_b32_e32 v2, 16, v39
	v_and_b32_e32 v3, 0xffff0000, v39
	v_pk_mul_f32 v[2:3], v[0:1], v[2:3] op_sel_hi:[0,1]
	v_cvt_pk_bf16_f32 v87, v2, v3
	v_add_u32_e32 v2, v162, v148
	ds_write_b128 v2, v[84:87]
	global_load_dwordx4 v[36:39], v[220:221], off offset:2048
	s_and_saveexec_b64 s[40:41], s[10:11]
	s_cbranch_execz .LBB0_838
	v_cvt_pk_bf16_f32 v0, v0, 0
	v_mov_b32_e32 v3, v1
	v_mov_b32_e32 v2, v0
	ds_write_b128 v162, v[0:3] offset:128
	ds_write_b128 v162, v[0:3] offset:144
.LBB0_838:
	s_or_b64 exec, exec, s[40:41]
	v_add_u32_e32 v0, v149, v163
	s_waitcnt vmcnt(9)
	ds_write_b128 v0, v[40:43]
	v_lshlrev_b32_e32 v2, 16, v40
	v_and_b32_e32 v3, 0xffff0000, v40
	v_lshlrev_b32_e32 v84, 16, v41
	v_and_b32_e32 v85, 0xffff0000, v41
	v_sub_f32_e32 v0, v225, v143
	v_mul_f32_e32 v0, 0x3fb8aa3b, v0
	v_exp_f32_e32 v0, v0
	s_nop 0
	v_pk_mul_f32 v[2:3], v[0:1], v[2:3] op_sel_hi:[0,1]
	v_pk_mul_f32 v[86:87], v[0:1], v[84:85] op_sel_hi:[0,1]
	v_cvt_pk_bf16_f32 v84, v2, v3
	v_lshlrev_b32_e32 v2, 16, v42
	v_and_b32_e32 v3, 0xffff0000, v42
	v_pk_mul_f32 v[2:3], v[0:1], v[2:3] op_sel_hi:[0,1]
	v_cvt_pk_bf16_f32 v85, v86, v87
	v_cvt_pk_bf16_f32 v86, v2, v3
	v_lshlrev_b32_e32 v2, 16, v43
	v_and_b32_e32 v3, 0xffff0000, v43
	v_pk_mul_f32 v[2:3], v[0:1], v[2:3] op_sel_hi:[0,1]
	v_cvt_pk_bf16_f32 v87, v2, v3
	v_add_u32_e32 v2, v164, v148
	ds_write_b128 v2, v[84:87]
	global_load_dwordx4 v[40:43], v[222:223], off offset:2048
	s_and_saveexec_b64 s[40:41], s[10:11]
	s_cbranch_execz .LBB0_840
	v_cvt_pk_bf16_f32 v0, v0, 0
	v_mov_b32_e32 v3, v1
	v_mov_b32_e32 v2, v0
	ds_write_b128 v164, v[0:3] offset:128
	ds_write_b128 v164, v[0:3] offset:144
.LBB0_840:
	s_or_b64 exec, exec, s[40:41]
	s_add_i32 s49, s49, 1
	s_cmp_ge_u32 s49, s47
	s_cselect_b64 s[40:41], -1, 0
	s_cmp_lt_u32 s49, s47
	s_cbranch_scc0 .LBB0_843
	s_and_b64 vcc, exec, s[0:1]
	s_cbranch_vccz .LBB0_843
	v_sub_u32_e32 v3, 0, v144
	v_add_u32_e32 v0, s48, v144
	v_add_u32_e32 v84, s46, v3
	v_add_u32_e32 v2, 0x80, v0
	v_add_u32_e32 v3, 0xffffff7f, v84
	v_cndmask_b32_e64 v2, v3, v2, s[90:91]
	v_add_u32_e32 v84, 0xffffff7e, v84
	v_add_u32_e32 v0, 0x81, v0
	v_ashrrev_i32_e32 v3, 31, v2
	v_cndmask_b32_e64 v84, v84, v0, s[90:91]
	v_lshl_add_u64 v[2:3], v[2:3], 0, s[96:97]
	v_readlane_b32 s92, v255, 26
	v_ashrrev_i32_e32 v85, 31, v84
	v_lshlrev_b64 v[2:3], 6, v[2:3]
	v_readlane_b32 s93, v255, 27
	v_lshl_add_u64 v[84:85], v[84:85], 0, s[96:97]
	v_lshlrev_b64 v[84:85], 6, v[84:85]
	v_lshl_add_u64 v[2:3], s[92:93], 0, v[2:3]
	v_lshl_add_u64 v[84:85], s[92:93], 0, v[84:85]
	v_lshl_add_u64 v[86:87], v[2:3], 0, s[36:37]
	v_lshl_add_u64 v[2:3], v[2:3], 0, s[38:39]
	global_load_dword v132, v[86:87], off
	global_load_dword v123, v[2:3], off
	v_lshl_add_u64 v[2:3], v[84:85], 0, s[36:37]
	global_load_dword v133, v[2:3], off
	v_lshl_add_u64 v[2:3], v[84:85], 0, s[38:39]
	global_load_dword v207, v[2:3], off

; DI unsigned pk2(float lo, float hi) { f32x2 v = {lo, hi}; bf16x2_t b = __builtin_convertvector(v, bf16x2_t); return __builtin_bit_cast(unsigned, b); }
; DI void mlstm_phase(LAS unsigned char* lds, const bf16_t* proj, const float* gates, bf16_t* Hfw, bf16_t* Hbw, int G, int bid) {
;     ...
;                 const float dn = __shfl(nacc[4][0], fr);
;                 const float dd = fmaxf(fabsf(dn), __expf(-(bt + Mt)));
;                 const float inv = 1.0f / dd;
;                 bf16_t* op = Hout + MTOK(c * 128 + t) * D + hh * 256 + sl * 64 + 4 * fq;
;                 u32x2 w[4];
; #pragma unroll
;                 for (int dt = 0; dt < 4; ++dt) { w[dt].x = pk2(nacc[dt][0] * inv, nacc[dt][1] * inv); w[dt].y = pk2(nacc[dt][2] * inv, nacc[dt][3] * inv); }
;                 { const bool odd = (fq & 1) != 0;
;                   const u32x2 s01 = odd ? w[0] : w[1], s23 = odd ? w[2] : w[3];
;                   u32x2 r01, r23; r01.x = __shfl_xor(s01.x, 16); r01.y = __shfl_xor(s01.y, 16); r23.x = __shfl_xor(s23.x, 16); r23.y = __shfl_xor(s23.y, 16);
;                   const u32x4 o0 = odd ? (u32x4){r01.x, r01.y, w[1].x, w[1].y} : (u32x4){w[0].x, w[0].y, r01.x, r01.y};
;                   const u32x4 o1 = odd ? (u32x4){r23.x, r23.y, w[3].x, w[3].y} : (u32x4){w[2].x, w[2].y, r23.x, r23.y};
;                   bf16_t* ob = op - 4 * fq + 8 * (fq >> 1) + (odd ? 16 : 0);
;                   __builtin_nontemporal_store(o0, (u32x4*)ob); __builtin_nontemporal_store(o1, (u32x4*)(ob + 32)); }
;             }
;             if (nown > 0) {
;                 const float decay = __expf(mp - M127);
; #pragma unroll
;                 for (int dt = 0; dt < 5; ++dt) { Creg[0][dt] = Creg[0][dt] * decay; Creg[1][dt] = Creg[1][dt] * decay; }
; #pragma unroll
;                 for (int jj = 0; jj < 4; ++jj) {
;                     bf16x8 kb0, kb1, af[5];
;                     const int sr = 32 * jj + 4 * fq + (fr >> 2);
;                     kb0 = tr_pair(Ks + sr * MQ_STRIDE + (16 * wid + 4 * (fr & 3)) * 2, Ks + (sr + 16) * MQ_STRIDE + (16 * wid + 4 * (fr & 3)) * 2);
;                     kb1 = kb0;
;                     if (nown == 2) kb1 = tr_pair(Ks + sr * MQ_STRIDE + (16 * (wid + 6) + 4 * (fr & 3)) * 2, Ks + (sr + 16) * MQ_STRIDE + (16 * (wid + 6) + 4 * (fr & 3)) * 2);
.LBB0_851:
	v_and_b32_e32 v0, 64, v193
	v_add_f32_e32 v2, v2, v3
	v_mul_f32_e32 v2, 0xbfb8aa3b, v2
	v_exp_f32_e32 v2, v2
	s_nop 4
	v_max_f32_e64 v3, |v104|, |v104|
	v_max_f32_e32 v2, v3, v2
	v_div_scale_f32 v3, s[92:93], v2, v2, 1.0
	v_rcp_f32_e32 v100, v3
	v_div_scale_f32 v101, vcc, 1.0, v2, 1.0
	v_fma_f32 v102, -v3, v100, 1.0
	v_fmac_f32_e32 v100, v102, v100
	v_mul_f32_e32 v102, v101, v100
	v_fma_f32 v103, -v3, v102, v101
	v_fmac_f32_e32 v102, v103, v100
	v_fma_f32 v3, -v3, v102, v101
	v_div_fmas_f32 v3, v3, v100, v102
	v_div_fixup_f32 v2, v3, v2, 1.0
	v_add_u32_e32 v3, s48, v150
	v_pk_mul_f32 v[84:85], v[84:85], v[2:3] op_sel_hi:[1,0]
	v_add_u32_e32 v100, s46, v178
	v_cvt_pk_bf16_f32 v102, v84, v85
	v_pk_mul_f32 v[84:85], v[86:87], v[2:3] op_sel_hi:[1,0]
	v_cndmask_b32_e64 v100, v100, v3, s[90:91]
	v_cvt_pk_bf16_f32 v103, v84, v85
	v_pk_mul_f32 v[84:85], v[88:89], v[2:3] op_sel_hi:[1,0]
	v_ashrrev_i32_e32 v101, 31, v100
	v_cvt_pk_bf16_f32 v86, v84, v85
	v_pk_mul_f32 v[84:85], v[90:91], v[2:3] op_sel_hi:[1,0]
	v_lshl_add_u64 v[100:101], v[100:101], 0, s[96:97]
	v_cvt_pk_bf16_f32 v87, v84, v85
	v_pk_mul_f32 v[84:85], v[92:93], v[2:3] op_sel_hi:[1,0]
	v_xor_b32_e32 v93, 16, v193
	v_cvt_pk_bf16_f32 v88, v84, v85
	v_pk_mul_f32 v[84:85], v[94:95], v[2:3] op_sel_hi:[1,0]
	v_add_u32_e32 v94, 64, v0
	v_cmp_lt_i32_e32 vcc, v93, v94
	v_cvt_pk_bf16_f32 v89, v84, v85
	v_pk_mul_f32 v[84:85], v[96:97], v[2:3] op_sel_hi:[1,0]
	v_pk_mul_f32 v[2:3], v[98:99], v[2:3] op_sel_hi:[1,0]
	v_cndmask_b32_e32 v93, v193, v93, vcc
	v_cvt_pk_bf16_f32 v90, v84, v85
	v_cvt_pk_bf16_f32 v91, v2, v3
	v_cndmask_b32_e64 v84, v103, v87, s[12:13]
	v_cndmask_b32_e64 v85, v102, v86, s[12:13]
	v_lshlrev_b32_e32 v93, 2, v93
	v_cndmask_b32_e64 v92, v89, v91, s[12:13]
	ds_bpermute_b32 v84, v93, v84
	ds_bpermute_b32 v94, v93, v85
	v_cndmask_b32_e64 v85, v88, v90, s[12:13]
	ds_bpermute_b32 v95, v93, v85
	ds_bpermute_b32 v92, v93, v92
	v_lshlrev_b64 v[2:3], 11, v[100:101]
	s_waitcnt lgkmcnt(3)
	v_cndmask_b32_e64 v87, v87, v84, s[12:13]
	s_waitcnt lgkmcnt(2)
	v_cndmask_b32_e64 v86, v86, v94, s[12:13]
	v_cndmask_b32_e64 v85, v84, v103, s[12:13]
	v_cndmask_b32_e64 v84, v94, v102, s[12:13]
	v_lshl_add_u64 v[2:3], v[136:137], 0, v[2:3]
	s_waitcnt lgkmcnt(0)
	v_cndmask_b32_e64 v91, v91, v92, s[12:13]
	v_cndmask_b32_e64 v90, v90, v95, s[12:13]
	v_cndmask_b32_e64 v89, v92, v89, s[12:13]
	v_cndmask_b32_e64 v88, v95, v88, s[12:13]
	global_store_dwordx4 v[2:3], v[84:87], off nt
	global_store_dwordx4 v[2:3], v[88:91], off offset:64 nt
	v_cndmask_b32_e64 v2, 0, 1, s[6:7]
	v_cmp_ne_u32_e64 s[94:95], 1, v2
	v_cndmask_b32_e64 v2, 0, 1, s[4:5]
	s_andn2_b64 vcc, exec, s[6:7]
	v_cmp_ne_u32_e64 s[92:93], 1, v2
	s_cbranch_vccnz .LBB0_869
	v_add_u32_e32 v2, v165, v152
	ds_read_b64_tr_b16 v[84:85], v2 offset:34816
	v_add_u32_e32 v2, v166, v152
	ds_read_b64_tr_b16 v[86:87], v2 offset:34816
	s_and_b64 vcc, exec, s[92:93]
	s_waitcnt lgkmcnt(1)
	v_mov_b32_e32 v88, v84
	v_mov_b32_e32 v89, v85
	s_waitcnt lgkmcnt(0)
	v_mov_b32_e32 v90, v86
	v_mov_b32_e32 v91, v87
	s_cbranch_vccnz .LBB0_854
	v_add_u32_e32 v2, v165, v154
	v_add_u32_e32 v3, v166, v154
	ds_read_b64_tr_b16 v[88:89], v2 offset:34816
	ds_read_b64_tr_b16 v[90:91], v3 offset:34816
